# attention band loop: causal mask compares use inline constants against (qrel - kb) with rotating SGPR pairs (2 issue slots per element instead of 4)
# speedup vs baseline: 1.0053x; 1.0053x over previous
.LBB0_176:
	s_add_i32 s78, s4, -1
	s_lshl_b64 s[16:17], s[78:79], 17
	s_add_i32 s28, s26, s4
	v_lshl_add_u64 v[34:35], v[208:209], 0, s[16:17]
	s_add_i32 s5, s24, s19
	s_add_i32 s16, s28, 2
	s_cmp_lt_i32 s16, 0
	s_mov_b32 m0, s5
	s_nop 0
	global_load_lds_dwordx4 v[34:35], off
	s_cbranch_scc1 .LBB0_178
	v_sub_u32_e32 v33, v219, v223
	v_cmp_le_i32_e64 vcc, 32, v33
	v_cmp_lt_i32_e64 s[100:101], 0, v33
	v_cmp_le_i32_e64 s[16:17], 0, v33
	v_cndmask_b32_e32 v48, v238, v48, vcc
	v_cndmask_b32_e64 v65, v238, v65, s[100:101]
	v_cndmask_b32_e64 v64, v238, v64, s[16:17]
	v_cmp_le_i32_e64 vcc, 33, v33
	v_cmp_le_i32_e64 s[100:101], 2, v33
	v_cmp_le_i32_e64 s[16:17], 34, v33
	v_cndmask_b32_e32 v49, v238, v49, vcc
	v_cndmask_b32_e64 v66, v238, v66, s[100:101]
	v_cndmask_b32_e64 v50, v238, v50, s[16:17]
	v_cmp_le_i32_e64 vcc, 3, v33
	v_cmp_le_i32_e64 s[100:101], 35, v33
	v_cmp_le_i32_e64 s[16:17], 8, v33
	v_cndmask_b32_e32 v67, v238, v67, vcc
	v_cndmask_b32_e64 v51, v238, v51, s[100:101]
	v_cndmask_b32_e64 v68, v238, v68, s[16:17]
	v_cmp_le_i32_e64 vcc, 40, v33
	v_cmp_le_i32_e64 s[100:101], 9, v33
	v_cmp_le_i32_e64 s[16:17], 41, v33
	v_cndmask_b32_e32 v52, v238, v52, vcc
	v_cndmask_b32_e64 v69, v238, v69, s[100:101]
	v_cndmask_b32_e64 v53, v238, v53, s[16:17]
	v_cmp_le_i32_e64 vcc, 10, v33
	v_cmp_le_i32_e64 s[100:101], 42, v33
	v_cmp_le_i32_e64 s[16:17], 11, v33
	v_cndmask_b32_e32 v70, v238, v70, vcc
	v_cndmask_b32_e64 v54, v238, v54, s[100:101]
	v_cndmask_b32_e64 v71, v238, v71, s[16:17]
	v_cmp_le_i32_e64 vcc, 43, v33
	v_cmp_le_i32_e64 s[100:101], 16, v33
	v_cmp_le_i32_e64 s[16:17], 48, v33
	v_cndmask_b32_e32 v55, v238, v55, vcc
	v_cndmask_b32_e64 v72, v238, v72, s[100:101]
	v_cndmask_b32_e64 v56, v238, v56, s[16:17]
	v_cmp_le_i32_e64 vcc, 17, v33
	v_cmp_le_i32_e64 s[100:101], 49, v33
	v_cmp_le_i32_e64 s[16:17], 18, v33
	v_cndmask_b32_e32 v73, v238, v73, vcc
	v_cndmask_b32_e64 v57, v238, v57, s[100:101]
	v_cndmask_b32_e64 v74, v238, v74, s[16:17]
	v_cmp_le_i32_e64 vcc, 50, v33
	v_cmp_le_i32_e64 s[100:101], 19, v33
	v_cmp_le_i32_e64 s[16:17], 51, v33
	v_cndmask_b32_e32 v58, v238, v58, vcc
	v_cndmask_b32_e64 v75, v238, v75, s[100:101]
	v_cndmask_b32_e64 v59, v238, v59, s[16:17]
	v_cmp_le_i32_e64 vcc, 24, v33
	v_cmp_le_i32_e64 s[100:101], 56, v33
	v_cmp_le_i32_e64 s[16:17], 25, v33
	v_cndmask_b32_e32 v76, v238, v76, vcc
	v_cndmask_b32_e64 v60, v238, v60, s[100:101]
	v_cndmask_b32_e64 v77, v238, v77, s[16:17]
	v_cmp_le_i32_e64 vcc, 57, v33
	v_cmp_le_i32_e64 s[100:101], 26, v33
	v_cmp_le_i32_e64 s[16:17], 58, v33
	v_cndmask_b32_e32 v61, v238, v61, vcc
	v_cndmask_b32_e64 v78, v238, v78, s[100:101]
	v_cndmask_b32_e64 v62, v238, v62, s[16:17]
	v_cmp_le_i32_e64 vcc, 27, v33
	v_cmp_le_i32_e64 s[100:101], 59, v33
	s_nop 0
	v_cndmask_b32_e32 v79, v238, v79, vcc
	v_cndmask_b32_e64 v63, v238, v63, s[100:101]

.LBB0_187:
	s_add_i32 s28, s28, 3
	s_cmp_lt_i32 s28, 0
	s_cbranch_scc1 .LBB0_189
	v_sub_u32_e32 v245, v219, v223
	v_add_u32_e32 v245, 0xffffffc0, v245
	v_cmp_le_i32_e64 vcc, 32, v245
	v_cmp_lt_i32_e64 s[100:101], 0, v245
	s_nop 0
	v_cndmask_b32_e32 v32, v238, v32, vcc
	v_cndmask_b32_e64 v81, v238, v81, s[100:101]
	v_cmp_le_i32_e64 vcc, 0, v245
	v_cmp_le_i32_e64 s[100:101], 33, v245
	s_nop 0
	v_cndmask_b32_e32 v80, v238, v80, vcc
	v_cndmask_b32_e64 v33, v238, v33, s[100:101]
	v_cmp_le_i32_e64 vcc, 2, v245
	v_cmp_le_i32_e64 s[100:101], 34, v245
	s_nop 0
	v_cndmask_b32_e32 v82, v238, v82, vcc
	v_cndmask_b32_e64 v34, v238, v34, s[100:101]
	v_cmp_le_i32_e64 vcc, 3, v245
	v_cmp_le_i32_e64 s[100:101], 35, v245
	s_nop 0
	v_cndmask_b32_e32 v83, v238, v83, vcc
	v_cndmask_b32_e64 v35, v238, v35, s[100:101]
	v_cmp_le_i32_e64 vcc, 8, v245
	v_cmp_le_i32_e64 s[100:101], 40, v245
	s_nop 0
	v_cndmask_b32_e32 v84, v238, v84, vcc
	v_cndmask_b32_e64 v36, v238, v36, s[100:101]
	v_cmp_le_i32_e64 vcc, 9, v245
	v_cmp_le_i32_e64 s[100:101], 41, v245
	s_nop 0
	v_cndmask_b32_e32 v85, v238, v85, vcc
	v_cndmask_b32_e64 v37, v238, v37, s[100:101]
	v_cmp_le_i32_e64 vcc, 10, v245
	v_cmp_le_i32_e64 s[100:101], 42, v245
	s_nop 0
	v_cndmask_b32_e32 v86, v238, v86, vcc
	v_cndmask_b32_e64 v38, v238, v38, s[100:101]
	v_cmp_le_i32_e64 vcc, 11, v245
	v_cmp_le_i32_e64 s[100:101], 43, v245
	s_nop 0
	v_cndmask_b32_e32 v87, v238, v87, vcc
	v_cndmask_b32_e64 v39, v238, v39, s[100:101]
	v_cmp_le_i32_e64 vcc, 16, v245
	v_cmp_le_i32_e64 s[100:101], 48, v245
	s_nop 0
	v_cndmask_b32_e32 v88, v238, v88, vcc
	v_cndmask_b32_e64 v40, v238, v40, s[100:101]
	v_cmp_le_i32_e64 vcc, 17, v245
	v_cmp_le_i32_e64 s[100:101], 49, v245
	s_nop 0
	v_cndmask_b32_e32 v89, v238, v89, vcc
	v_cndmask_b32_e64 v41, v238, v41, s[100:101]
	v_cmp_le_i32_e64 vcc, 18, v245
	v_cmp_le_i32_e64 s[100:101], 50, v245
	s_nop 0
	v_cndmask_b32_e32 v90, v238, v90, vcc
	v_cndmask_b32_e64 v42, v238, v42, s[100:101]
	v_cmp_le_i32_e64 vcc, 19, v245
	v_cmp_le_i32_e64 s[100:101], 51, v245
	s_nop 0
	v_cndmask_b32_e32 v91, v238, v91, vcc
	v_cndmask_b32_e64 v43, v238, v43, s[100:101]
	v_cmp_le_i32_e64 vcc, 24, v245
	v_cmp_le_i32_e64 s[100:101], 56, v245
	s_nop 0
	v_cndmask_b32_e32 v92, v238, v92, vcc
	v_cndmask_b32_e64 v44, v238, v44, s[100:101]
	v_cmp_le_i32_e64 vcc, 25, v245
	v_cmp_le_i32_e64 s[100:101], 57, v245
	s_nop 0
	v_cndmask_b32_e32 v93, v238, v93, vcc
	v_cndmask_b32_e64 v45, v238, v45, s[100:101]
	v_cmp_le_i32_e64 vcc, 26, v245
	v_cmp_le_i32_e64 s[100:101], 58, v245
	s_nop 0
	v_cndmask_b32_e32 v94, v238, v94, vcc
	v_cndmask_b32_e64 v46, v238, v46, s[100:101]
	v_cmp_le_i32_e64 vcc, 27, v245
	v_cmp_le_i32_e64 s[100:101], 59, v245
	s_nop 0
	v_cndmask_b32_e32 v95, v238, v95, vcc
	v_cndmask_b32_e64 v47, v238, v47, s[100:101]
